# v4 plus: attention tile loop unrolled 2x (even/odd LDS buffer via immediate offsets), per-tile address toggles removed
# speedup vs baseline: 1.0002x; 1.0002x over previous
; #define LAS __attribute__((address_space(3)))
; template <bool SHIFT> DI void phase_attn2(const Params& p, const Grp& G, int layer, LAS unsigned char* lds, int tid, int wave, int lane, int vcu, bool dry) {
;     ...
;         const int qb = u % NQB, bh = u / NQB, h = bh & 3, b = bh >> 2; const size_t seq0 = (size_t)b * G.S; const size_t qrow0 = seq0 + (size_t)qb * 256;
;         bf16x8 qf[2][4];
;         int lq = (int)__builtin_amdgcn_mbcnt_hi(~0u, __builtin_amdgcn_mbcnt_lo(~0u, 0u)); asm volatile("" : "+v"(lq));
; #pragma unroll
;         for (int rbq = 0; rbq < 2; ++rbq) { const bf16_t* qp = mix + (qrow0 + 64 * qg + 32 * rbq + (lq & 31)) * MIXW + h * 128 + c * 64 + 8 * (lq >> 5);
; #pragma unroll
;           for (int d0 = 0; d0 < 4; ++d0) qf[rbq][d0] = *(const bf16x8*)(qp + 16 * d0); }
;         LAS unsigned char* Qs = lds + AT2_QS + wave * 8192 + lane * 16;
;         const bf16_t* kg = rest + seq0 * RESTW + R_DK + h * 128; const bf16_t* vg = rest + seq0 * RESTW + R_DV + h * 128;
;         __syncthreads();
;     ...
;         { unsigned dfl = doff0; asm volatile("" : "+v"(dfl)); AT2_DMA(0, 0); }
; #pragma unroll
;         for (int rbq = 0; rbq < 2; ++rbq)
; #pragma unroll
;             for (int d0 = 0; d0 < 4; ++d0) *(LAS bf16x8*)(Qs + (rbq * 4 + d0) * 1024) = qf[rbq][d0];
;         asm volatile("s_waitcnt vmcnt(0)" ::: "memory");
;         __syncthreads();
;         f32x16 o[2][4];
; #pragma unroll
;         for (int a = 0; a < 2; ++a)
; #pragma unroll
;             for (int cb = 0; cb < 4; ++cb) o[a][cb] = f32x16{};
.LBB0_377:
	s_abs_i32 s1, s58
	s_mul_hi_u32 s8, s1, s55
	s_mul_i32 s9, s8, s53
	s_ashr_i32 s0, s58, 31
	s_sub_i32 s1, s1, s9
	s_xor_b32 s0, s0, s54
	s_add_i32 s9, s8, 1
	s_sub_i32 s10, s1, s53
	s_cmp_ge_u32 s1, s53
	s_cselect_b32 s8, s9, s8
	s_cselect_b32 s1, s10, s1
	s_add_i32 s9, s8, 1
	s_cmp_ge_u32 s1, s53
	s_cselect_b32 s1, s9, s8
	s_xor_b32 s1, s1, s0
	s_sub_i32 s10, s1, s0
	s_mul_i32 s0, s10, s14
	s_sub_i32 s8, s58, s0
	s_ashr_i32 s0, s10, 2
	s_ashr_i32 s1, s0, 31
	v_readlane_b32 s9, v255, 40
	s_lshl_b64 s[0:1], s[0:1], s9
	s_ashr_i32 s9, s8, 31
	s_lshl_b64 s[8:9], s[8:9], 8
	s_add_u32 s40, s0, s8
	s_addc_u32 s41, s1, s9
	v_mov_b32_e32 v2, v245
	s_lshl_b32 s8, s10, 7
	s_and_b32 s59, s8, 0x180
	v_and_or_b32 v0, v2, 31, s13
	s_lshl_b32 s11, s59, 1
	v_ashrrev_i32_e32 v2, 2, v2
	s_add_u32 s8, s16, s11
	v_and_b32_e32 v2, -8, v2
	s_addc_u32 s9, s17, 0
	v_ashrrev_i32_e32 v3, 31, v2
	v_lshl_add_u64 v[2:3], v[2:3], 1, s[8:9]
	s_mulk_i32 s1, 0x1400
	s_mul_hi_u32 s9, s0, 0x1400
	v_or_b32_e32 v0, s40, v0
	v_mov_b32_e32 v1, s41
	s_mul_i32 s30, s0, 0x1400
	s_add_i32 s9, s9, s1
	v_lshlrev_b64 v[0:1], 11, v[0:1]
	s_add_u32 s0, s48, s30
	v_lshl_add_u64 v[16:17], v[2:3], 0, v[0:1]
	s_mov_b32 s8, 0x10000
	s_addc_u32 s1, s49, s9
	v_add_co_u32_e32 v28, vcc, s8, v16
	s_add_u32 s0, s0, s11
	s_nop 0
	v_addc_co_u32_e32 v29, vcc, 0, v17, vcc
	v_mov_b32_e32 v192, v219
	s_addc_u32 s1, s1, 0
	s_mov_b32 m0, s33
	global_load_dwordx4 v[0:3], v[16:17], off
	global_load_dwordx4 v[4:7], v[16:17], off offset:32
	global_load_dwordx4 v[8:11], v[16:17], off offset:64
	global_load_dwordx4 v[12:15], v[16:17], off offset:96
	s_nop 0
	global_load_dwordx4 v[16:19], v[28:29], off
	global_load_dwordx4 v[20:23], v[28:29], off offset:32
	global_load_dwordx4 v[24:27], v[28:29], off offset:64
	s_nop 0
	global_load_dwordx4 v[28:31], v[28:29], off offset:96
	s_barrier
	s_mov_b64 s[84:85], 0x400
	v_lshl_add_u64 v[34:35], s[0:1], 0, v[192:193]
	global_load_lds_dwordx4 v192, s[0:1]
	s_add_i32 m0, s33, 0x4000
	v_lshl_add_u64 v[34:35], v[34:35], 0, s[84:85]
	v_mov_b32_e32 v33, v193
	v_xad_u32 v32, v192, 16, v244
	global_load_lds_dwordx4 v[34:35], off
	s_add_i32 m0, s33, 0x400
	v_lshl_add_u64 v[36:37], s[0:1], 0, v[32:33]
	global_load_lds_dwordx4 v32, s[0:1]
	v_readlane_b32 s0, v254, 37
	v_lshl_add_u64 v[34:35], v[36:37], 0, s[84:85]
	s_mov_b32 m0, s0
	s_and_b32 s10, s10, 3
	global_load_lds_dwordx4 v[34:35], off
	s_lshl_b32 s10, s10, 8
	s_or_b32 s10, s30, s10
	v_mov_b32_e32 v64, 0
	s_add_u32 s30, s56, s10
	s_mov_b32 s8, 0
	v_mov_b32_e32 v222, v221
	s_mov_b32 s38, 0
	v_mov_b32_e32 v65, v64
	v_mov_b32_e32 v66, v64
	s_addc_u32 s31, s57, s9
	v_mov_b32_e32 v67, v64
	v_mov_b32_e32 v68, v64
	v_mov_b32_e32 v69, v64
	v_mov_b32_e32 v70, v64
	v_mov_b32_e32 v71, v64
	v_mov_b32_e32 v72, v64
	v_mov_b32_e32 v73, v64
	v_mov_b32_e32 v74, v64
	v_mov_b32_e32 v75, v64
	v_mov_b32_e32 v76, v64
	v_mov_b32_e32 v77, v64
	v_mov_b32_e32 v78, v64
	v_mov_b32_e32 v79, v64
	v_mov_b32_e32 v80, v64
	s_waitcnt vmcnt(0)
	ds_write_b128 v221, v[0:3]
	ds_write_b128 v221, v[4:7] offset:1024
	ds_write_b128 v221, v[8:11] offset:2048
	ds_write_b128 v221, v[12:15] offset:3072
	ds_write_b128 v221, v[16:19] offset:4096
	ds_write_b128 v221, v[20:23] offset:5120
	ds_write_b128 v221, v[24:27] offset:6144
	ds_write_b128 v221, v[28:31] offset:7168
	s_waitcnt vmcnt(0)
	v_mov_b32_e32 v81, v64
	v_mov_b32_e32 v82, v64
	v_mov_b32_e32 v83, v64
	v_mov_b32_e32 v84, v64
	v_mov_b32_e32 v85, v64
	v_mov_b32_e32 v86, v64
	v_mov_b32_e32 v87, v64
	v_mov_b32_e32 v88, v64
	v_mov_b32_e32 v89, v64
	v_mov_b32_e32 v90, v64
	v_mov_b32_e32 v91, v64
	v_mov_b32_e32 v92, v64
	v_mov_b32_e32 v93, v64
	v_mov_b32_e32 v94, v64
	v_mov_b32_e32 v95, v64
	v_mov_b32_e32 v96, v64
	v_mov_b32_e32 v97, v64
	v_mov_b32_e32 v98, v64
	v_mov_b32_e32 v99, v64
	v_mov_b32_e32 v100, v64
	v_mov_b32_e32 v101, v64
	v_mov_b32_e32 v102, v64
	v_mov_b32_e32 v103, v64
	v_mov_b32_e32 v104, v64
	v_mov_b32_e32 v105, v64
	v_mov_b32_e32 v106, v64
	v_mov_b32_e32 v107, v64
	v_mov_b32_e32 v108, v64
	v_mov_b32_e32 v109, v64
	v_mov_b32_e32 v110, v64
	v_mov_b32_e32 v111, v64
	v_mov_b32_e32 v112, v64
	v_mov_b32_e32 v113, v64
	v_mov_b32_e32 v114, v64
	v_mov_b32_e32 v115, v64
	v_mov_b32_e32 v116, v64
	v_mov_b32_e32 v117, v64
	v_mov_b32_e32 v118, v64
	v_mov_b32_e32 v119, v64
	v_mov_b32_e32 v120, v64
	v_mov_b32_e32 v121, v64
	v_mov_b32_e32 v122, v64
	v_mov_b32_e32 v123, v64
	v_mov_b32_e32 v124, v64
	v_mov_b32_e32 v125, v64
	v_mov_b32_e32 v126, v64
	v_mov_b32_e32 v127, v64
	v_mov_b32_e32 v0, v64
	v_mov_b32_e32 v1, v64
	v_mov_b32_e32 v2, v64
	v_mov_b32_e32 v3, v64
	v_mov_b32_e32 v4, v64
	v_mov_b32_e32 v5, v64
	v_mov_b32_e32 v6, v64
	v_mov_b32_e32 v7, v64
	v_mov_b32_e32 v8, v64
	v_mov_b32_e32 v9, v64
	v_mov_b32_e32 v10, v64
	v_mov_b32_e32 v11, v64
	v_mov_b32_e32 v12, v64
	v_mov_b32_e32 v13, v64
	v_mov_b32_e32 v14, v64
	v_mov_b32_e32 v15, v64
	v_mov_b32_e32 v16, v64
	v_mov_b32_e32 v17, v64
	v_mov_b32_e32 v18, v64
	v_mov_b32_e32 v19, v64
	v_mov_b32_e32 v20, v64
	v_mov_b32_e32 v21, v64
	v_mov_b32_e32 v22, v64
	v_mov_b32_e32 v23, v64
	v_mov_b32_e32 v24, v64
	v_mov_b32_e32 v25, v64
	v_mov_b32_e32 v26, v64
	v_mov_b32_e32 v27, v64
	v_mov_b32_e32 v28, v64
	v_mov_b32_e32 v29, v64
	v_mov_b32_e32 v30, v64
	v_mov_b32_e32 v31, v64
	v_mov_b32_e32 v32, v64
	v_mov_b32_e32 v33, v64
	v_mov_b32_e32 v34, v64
	v_mov_b32_e32 v35, v64
	v_mov_b32_e32 v36, v64
	v_mov_b32_e32 v37, v64
	v_mov_b32_e32 v38, v64
	v_mov_b32_e32 v39, v64
	v_mov_b32_e32 v40, v64
	v_mov_b32_e32 v41, v64
	v_mov_b32_e32 v42, v64
	v_mov_b32_e32 v43, v64
	v_mov_b32_e32 v44, v64
	v_mov_b32_e32 v45, v64
	v_mov_b32_e32 v46, v64
	v_mov_b32_e32 v47, v64
	v_mov_b32_e32 v48, v64
	v_mov_b32_e32 v49, v64
	v_mov_b32_e32 v50, v64
	v_mov_b32_e32 v51, v64
	v_mov_b32_e32 v52, v64
	v_mov_b32_e32 v53, v64
	v_mov_b32_e32 v54, v64
	v_mov_b32_e32 v55, v64
	v_mov_b32_e32 v56, v64
	v_mov_b32_e32 v57, v64
	v_mov_b32_e32 v58, v64
	v_mov_b32_e32 v59, v64
	v_mov_b32_e32 v60, v64
	v_mov_b32_e32 v61, v64
	v_mov_b32_e32 v62, v64
	v_mov_b32_e32 v63, v64
	v_mov_b32_e32 v164, v64
	v_mov_b32_e32 v165, v64
	v_xor_b32_e32 v236, 32, v217
	v_xor_b32_e32 v237, 64, v217
	v_xor_b32_e32 v238, 0x60, v217
	v_xor_b32_e32 v239, 32, v218
	v_xor_b32_e32 v240, 64, v218
	v_xor_b32_e32 v241, 0x60, v218
	v_xor_b32_e32 v248, 0x80, v218
	v_xor_b32_e32 v249, 0xa0, v218
	v_xor_b32_e32 v250, 0xc0, v218
	v_xor_b32_e32 v251, 0xe0, v218
	v_xad_u32 v252, v219, 16, v244
	s_waitcnt lgkmcnt(0)
	s_barrier
	s_branch .LBB0_379
; #define SB() __builtin_amdgcn_sched_barrier(0)
; #define EXPACK(sc_, rbq_, p0_, p1_) do { float ps_ = 0.f; \
;                 _Pragma("unroll") for (int r = 0; r < 16; ++r) { sc_[r] = __builtin_amdgcn_exp2f(SHIFT ? sc_[r] - bound2 : sc_[r]); ps_ += sc_[r]; } \
;                 lsum[rbq_] += ps_; p0_ = pack8(sc_, 0); p1_ = pack8(sc_, 1); } while (0)
; #define BLOAD(B_, ks_) do { asm volatile("" : "+v"(v0l)); _Pragma("unroll") for (int cb = 0; cb < 4; ++cb) B_[cb] = BFRAG(ks_, cb); SB(); } while (0)
; #define PVMMA(B_, pA_, pB_) do { _Pragma("unroll") for (int cb = 0; cb < 4; ++cb) { o[0][cb] = MFMA32(pA_, B_[cb], o[0][cb]); o[1][cb] = MFMA32(pB_, B_[cb], o[1][cb]); } } while (0)
; template <bool SHIFT> DI void phase_attn2(const Params& p, const Grp& G, int layer, LAS unsigned char* lds, int tid, int wave, int lane, int vcu, bool dry) {
;     ...
;             {
;                 f32x16 s0, s1; bf16x8 pa00, pa01, pa10, pa11; bf16x8 kfs[4], qfs[4];
;                 CHAIN(s0, 0, 0, true, true); CHAIN(s1, 0, 1, false, true);
;                 EXPACK(s0, 0, pa00, pa01); EXPACK(s1, 1, pa10, pa11);
;                 SB();
;                 CHAIN(s1, 1, 1, true, false); CHAIN(s0, 1, 0, false, true);
;                 bf16x8 pb00, pb01, pb10, pb11; bf16x8 B[4];
;                 BLOAD(B, 0);
;                 PVMMA(B, pa00, pa10); EXPACK(s0, 0, pb00, pb01);
;                 SB();
;                 BLOAD(B, 1);
;                 PVMMA(B, pa01, pa11); EXPACK(s1, 1, pb10, pb11);
;                 SB();
;                 BLOAD(B, 2);
;                 PVMMA(B, pb00, pb10);
.LBB0_378:
	ds_read_b128 v[128:131], v217
	ds_read_b128 v[160:163], v236
	ds_read_b128 v[166:169], v237
	ds_read_b128 v[170:173], v238
	ds_read_b128 v[132:135], v222
	ds_read_b128 v[136:139], v222 offset:1024
	ds_read_b128 v[140:143], v222 offset:2048
	ds_read_b128 v[174:177], v222 offset:3072
	s_waitcnt lgkmcnt(0)
	v_mfma_f32_32x32x16_bf16 v[144:159], v[128:131], v[132:135], 0
	v_mfma_f32_32x32x16_bf16 v[144:159], v[160:163], v[136:139], v[144:159]
	v_mfma_f32_32x32x16_bf16 v[144:159], v[166:169], v[140:143], v[144:159]
	v_mfma_f32_32x32x16_bf16 v[144:159], v[170:173], v[174:177], v[144:159]
	ds_read_b128 v[174:177], v222 offset:4096
	ds_read_b128 v[178:181], v222 offset:5120
	ds_read_b128 v[182:185], v222 offset:6144
	ds_read_b128 v[224:227], v222 offset:7168
	s_waitcnt lgkmcnt(0)
	v_mfma_f32_32x32x16_bf16 v[128:143], v[128:131], v[174:177], 0
	v_mfma_f32_32x32x16_bf16 v[128:143], v[160:163], v[178:181], v[128:143]
	v_mfma_f32_32x32x16_bf16 v[128:143], v[166:169], v[182:185], v[128:143]
	v_mfma_f32_32x32x16_bf16 v[128:143], v[170:173], v[224:227], v[128:143]
	s_nop 2
	v_exp_f32_e32 v144, v144
	v_exp_f32_e32 v145, v145
	v_exp_f32_e32 v146, v146
	v_exp_f32_e32 v147, v147
	v_exp_f32_e32 v148, v148
	s_nop 3
	v_exp_f32_e32 v189, v135
	v_exp_f32_e32 v149, v149
	v_add_f32_e32 v135, v145, v144
	v_exp_f32_e32 v150, v150
	v_exp_f32_e32 v188, v151
	v_exp_f32_e32 v128, v128
	v_exp_f32_e32 v129, v129
	v_exp_f32_e32 v130, v130
	v_exp_f32_e32 v131, v131
	v_exp_f32_e32 v132, v132
	v_exp_f32_e32 v133, v133
	v_exp_f32_e32 v134, v134
	v_add_f32_e32 v135, v146, v135
	v_add_f32_e32 v135, v147, v135
	v_add_f32_e32 v135, v148, v135
	v_add_f32_e32 v135, v149, v135
	v_exp_f32_e32 v208, v152
	v_exp_f32_e32 v206, v153
	v_exp_f32_e32 v204, v154
	v_exp_f32_e32 v202, v155
	v_exp_f32_e32 v200, v156
	v_exp_f32_e32 v198, v157
	v_exp_f32_e32 v196, v158
	v_exp_f32_e32 v190, v159
	v_cvt_pk_bf16_f32 v160, v144, v145
	v_cvt_pk_bf16_f32 v161, v146, v147
	v_cvt_pk_bf16_f32 v162, v148, v149
	v_cvt_pk_bf16_f32 v163, v150, v188
	v_exp_f32_e32 v209, v136
	v_exp_f32_e32 v207, v137
	v_exp_f32_e32 v205, v138
	v_exp_f32_e32 v203, v139
	v_exp_f32_e32 v201, v140
	v_exp_f32_e32 v199, v141
	v_exp_f32_e32 v197, v142
	v_exp_f32_e32 v191, v143
	v_add_f32_e32 v210, v150, v135
	v_cvt_pk_bf16_f32 v166, v128, v129
	v_cvt_pk_bf16_f32 v167, v130, v131
	v_cvt_pk_bf16_f32 v168, v132, v133
	v_cvt_pk_bf16_f32 v169, v134, v189
	ds_read_b128 v[144:147], v217 offset:8192
	ds_read_b128 v[170:173], v236 offset:8192
	ds_read_b128 v[228:231], v237 offset:8192
	ds_read_b128 v[232:235], v238 offset:8192
	v_add_f32_e32 v128, v129, v128
	v_add_f32_e32 v128, v130, v128
	v_add_f32_e32 v128, v131, v128
	v_add_f32_e32 v128, v132, v128
	v_add_f32_e32 v128, v133, v128
	v_add_f32_e32 v211, v134, v128
	s_waitcnt lgkmcnt(0)
	v_mfma_f32_32x32x16_bf16 v[128:143], v[144:147], v[174:177], 0
	v_mfma_f32_32x32x16_bf16 v[128:143], v[170:173], v[178:181], v[128:143]
	v_mfma_f32_32x32x16_bf16 v[128:143], v[228:231], v[182:185], v[128:143]
	v_mfma_f32_32x32x16_bf16 v[128:143], v[232:235], v[224:227], v[128:143]
	ds_read_b128 v[148:151], v222
	ds_read_b128 v[174:177], v222 offset:1024
	ds_read_b128 v[178:181], v222 offset:2048
	ds_read_b128 v[182:185], v222 offset:3072
	s_waitcnt lgkmcnt(0)
	v_mfma_f32_32x32x16_bf16 v[144:159], v[144:147], v[148:151], 0
	v_mfma_f32_32x32x16_bf16 v[144:159], v[170:173], v[174:177], v[144:159]
	v_mfma_f32_32x32x16_bf16 v[144:159], v[228:231], v[178:181], v[144:159]
	v_mfma_f32_32x32x16_bf16 v[144:159], v[232:235], v[182:185], v[144:159]
	s_nop 4
	ds_read_b64_tr_b16 v[170:171], v218 offset:16384
	ds_read_b64_tr_b16 v[172:173], v239 offset:18432
	ds_read_b64_tr_b16 v[174:175], v240 offset:16384
	ds_read_b64_tr_b16 v[176:177], v241 offset:18432
	ds_read_b64_tr_b16 v[178:179], v248 offset:16384
	ds_read_b64_tr_b16 v[180:181], v249 offset:18432
	ds_read_b64_tr_b16 v[182:183], v250 offset:16384
	ds_read_b64_tr_b16 v[184:185], v251 offset:18432
	v_exp_f32_e32 v144, v144
	s_waitcnt lgkmcnt(6)
	v_mfma_f32_32x32x16_bf16 v[112:127], v[160:163], v[170:173], v[112:127]
	v_exp_f32_e32 v145, v145
	v_exp_f32_e32 v146, v146
	v_exp_f32_e32 v147, v147
	v_exp_f32_e32 v148, v148
	v_exp_f32_e32 v149, v149
	v_mfma_f32_32x32x16_bf16 v[0:15], v[166:169], v[170:173], v[0:15]
	v_exp_f32_e32 v170, v151
	v_exp_f32_e32 v172, v154
	s_waitcnt lgkmcnt(4)
	v_mfma_f32_32x32x16_bf16 v[96:111], v[160:163], v[174:177], v[96:111]
	v_mfma_f32_32x32x16_bf16 v[16:31], v[166:169], v[174:177], v[16:31]
	v_exp_f32_e32 v174, v153
	v_exp_f32_e32 v176, v156
	s_waitcnt lgkmcnt(2)
	v_mfma_f32_32x32x16_bf16 v[80:95], v[160:163], v[178:181], v[80:95]
	v_mfma_f32_32x32x16_bf16 v[32:47], v[166:169], v[178:181], v[32:47]
	v_exp_f32_e32 v178, v155
	v_exp_f32_e32 v180, v158
	s_waitcnt lgkmcnt(0)
; #define SB() __builtin_amdgcn_sched_barrier(0)
; #define EXPACK(sc_, rbq_, p0_, p1_) do { float ps_ = 0.f; \
;                 _Pragma("unroll") for (int r = 0; r < 16; ++r) { sc_[r] = __builtin_amdgcn_exp2f(SHIFT ? sc_[r] - bound2 : sc_[r]); ps_ += sc_[r]; } \
;                 lsum[rbq_] += ps_; p0_ = pack8(sc_, 0); p1_ = pack8(sc_, 1); } while (0)
; #define BLOAD(B_, ks_) do { asm volatile("" : "+v"(v0l)); _Pragma("unroll") for (int cb = 0; cb < 4; ++cb) B_[cb] = BFRAG(ks_, cb); SB(); } while (0)
; #define PVMMA(B_, pA_, pB_) do { _Pragma("unroll") for (int cb = 0; cb < 4; ++cb) { o[0][cb] = MFMA32(pA_, B_[cb], o[0][cb]); o[1][cb] = MFMA32(pB_, B_[cb], o[1][cb]); } } while (0)
; template <bool SHIFT> DI void phase_attn2(const Params& p, const Grp& G, int layer, LAS unsigned char* lds, int tid, int wave, int lane, int vcu, bool dry) {
;     ...
;                 PVMMA(B, pa00, pa10); EXPACK(s0, 0, pb00, pb01);
;                 SB();
;                 BLOAD(B, 1);
;                 PVMMA(B, pa01, pa11); EXPACK(s1, 1, pb10, pb11);
;                 SB();
;                 BLOAD(B, 2);
;                 PVMMA(B, pb00, pb10);
;                 SB();
;                 BLOAD(B, 3);
;                 PVMMA(B, pb01, pb11);
;                 SB();
;             }
;     ...
;             asm volatile("s_waitcnt vmcnt(0)" ::: "memory");
;             __syncthreads();
	v_mfma_f32_32x32x16_bf16 v[64:79], v[160:163], v[182:185], v[64:79]
	v_add_f32_e32 v160, v145, v144
	v_add_f32_e32 v160, v146, v160
	v_add_f32_e32 v160, v147, v160
	v_add_f32_e32 v160, v148, v160
	v_add_f32_e32 v186, v149, v160
	v_cvt_pk_bf16_f32 v144, v144, v145
	v_mfma_f32_32x32x16_bf16 v[48:63], v[166:169], v[182:185], v[48:63]
	v_exp_f32_e32 v166, v150
	v_exp_f32_e32 v168, v152
	v_exp_f32_e32 v182, v157
	v_exp_f32_e32 v184, v159
	v_cvt_pk_bf16_f32 v145, v146, v147
	v_cvt_pk_bf16_f32 v146, v148, v149
	s_nop 0
	ds_read_b64_tr_b16 v[160:161], v218 offset:20480
	ds_read_b64_tr_b16 v[162:163], v239 offset:22528
	ds_read_b64_tr_b16 v[156:157], v240 offset:20480
	ds_read_b64_tr_b16 v[158:159], v241 offset:22528
	ds_read_b64_tr_b16 v[152:153], v248 offset:20480
	ds_read_b64_tr_b16 v[154:155], v249 offset:22528
	ds_read_b64_tr_b16 v[148:149], v250 offset:20480
	ds_read_b64_tr_b16 v[150:151], v251 offset:22528
	v_exp_f32_e32 v223, v128
	v_exp_f32_e32 v224, v129
	v_exp_f32_e32 v225, v130
	v_exp_f32_e32 v226, v131
	v_exp_f32_e32 v227, v132
	v_add_f32_e32 v128, v224, v223
	v_exp_f32_e32 v228, v133
	v_exp_f32_e32 v167, v134
	v_exp_f32_e32 v171, v135
	v_cvt_pk_bf16_f32 v132, v208, v206
	v_cvt_pk_bf16_f32 v133, v204, v202
	v_cvt_pk_bf16_f32 v134, v200, v198
	v_cvt_pk_bf16_f32 v135, v196, v190
	v_add_f32_e32 v128, v225, v128
	v_exp_f32_e32 v169, v136
	v_exp_f32_e32 v175, v137
	v_exp_f32_e32 v173, v138
	v_exp_f32_e32 v179, v139
	v_cvt_pk_bf16_f32 v136, v209, v207
	v_cvt_pk_bf16_f32 v137, v205, v203
	v_cvt_pk_bf16_f32 v138, v201, v199
	v_cvt_pk_bf16_f32 v139, v197, v191
	v_add_f32_e32 v128, v226, v128
	v_add_f32_e32 v128, v227, v128
	v_add_f32_e32 v187, v228, v128
	v_pk_add_f32 v[128:129], v[188:189], v[210:211]
	s_waitcnt lgkmcnt(6)
	v_mfma_f32_32x32x16_bf16 v[112:127], v[132:135], v[160:163], v[112:127]
	v_add_f32_e64 v128, v208, v128
	v_add_f32_e64 v129, v209, v129
	v_exp_f32_e32 v177, v140
	v_pk_add_f32 v[128:129], v[206:207], v[128:129]
	v_exp_f32_e32 v183, v141
	v_pk_add_f32 v[128:129], v[204:205], v[128:129]
	v_exp_f32_e32 v181, v142
	v_pk_add_f32 v[128:129], v[202:203], v[128:129]
	s_waitcnt lgkmcnt(4)
	v_mfma_f32_32x32x16_bf16 v[96:111], v[132:135], v[156:159], v[96:111]
	v_exp_f32_e32 v185, v143
	v_pk_add_f32 v[128:129], v[200:201], v[128:129]
	v_cvt_pk_bf16_f32 v147, v166, v170
	v_pk_add_f32 v[128:129], v[198:199], v[128:129]
	v_cvt_pk_bf16_f32 v130, v176, v182
	v_pk_add_f32 v[128:129], v[196:197], v[128:129]
	v_cvt_pk_bf16_f32 v131, v180, v184
	s_waitcnt lgkmcnt(2)
	v_mfma_f32_32x32x16_bf16 v[80:95], v[132:135], v[152:155], v[80:95]
	v_add_f32_e64 v128, v190, v128
	v_add_f32_e64 v129, v191, v129
	v_add_f32_e64 v140, v164, v128
	v_add_f32_e64 v141, v165, v129
	v_cvt_pk_bf16_f32 v128, v168, v174
	v_cvt_pk_bf16_f32 v129, v172, v178
	s_waitcnt lgkmcnt(0)
	v_mfma_f32_32x32x16_bf16 v[64:79], v[132:135], v[148:151], v[64:79]
	v_add_f32_e64 v132, v166, v186
	v_add_f32_e64 v133, v167, v187
	v_cvt_pk_bf16_f32 v134, v227, v228
	v_add_f32_e64 v132, v170, v132
	v_add_f32_e64 v133, v171, v133
	v_cvt_pk_bf16_f32 v135, v167, v171
	v_pk_add_f32 v[132:133], v[168:169], v[132:133]
	s_nop 0
	v_pk_add_f32 v[132:133], v[174:175], v[132:133]
	v_mfma_f32_32x32x16_bf16 v[0:15], v[136:139], v[160:163], v[0:15]
	v_add_f32_e64 v132, v172, v132
	v_add_f32_e64 v133, v173, v133
	v_add_f32_e64 v132, v178, v132
	v_add_f32_e64 v133, v179, v133
	v_add_f32_e64 v132, v176, v132
	v_add_f32_e64 v133, v177, v133
	v_pk_add_f32 v[132:133], v[182:183], v[132:133]
	v_mfma_f32_32x32x16_bf16 v[16:31], v[136:139], v[156:159], v[16:31]
	v_add_f32_e64 v132, v180, v132
	v_add_f32_e64 v133, v181, v133
	v_add_f32_e64 v142, v184, v132
	v_add_f32_e64 v143, v185, v133
	v_cvt_pk_bf16_f32 v132, v223, v224
	v_cvt_pk_bf16_f32 v133, v225, v226
	v_mfma_f32_32x32x16_bf16 v[32:47], v[136:139], v[152:155], v[32:47]
	v_mfma_f32_32x32x16_bf16 v[48:63], v[136:139], v[148:151], v[48:63]
	v_cvt_pk_bf16_f32 v136, v169, v175
	v_cvt_pk_bf16_f32 v137, v173, v179
	v_cvt_pk_bf16_f32 v138, v177, v183
	v_cvt_pk_bf16_f32 v139, v181, v185
	s_nop 0
	ds_read_b64_tr_b16 v[148:149], v218 offset:24576
	ds_read_b64_tr_b16 v[150:151], v239 offset:26624
	ds_read_b64_tr_b16 v[152:153], v240 offset:24576
	ds_read_b64_tr_b16 v[154:155], v241 offset:26624
	ds_read_b64_tr_b16 v[156:157], v248 offset:24576
	ds_read_b64_tr_b16 v[158:159], v249 offset:26624
	ds_read_b64_tr_b16 v[160:161], v250 offset:24576
	ds_read_b64_tr_b16 v[162:163], v251 offset:26624
	s_waitcnt lgkmcnt(6)
	v_mfma_f32_32x32x16_bf16 v[112:127], v[144:147], v[148:151], v[112:127]
	v_add_f32_e64 v164, v140, v142
	v_add_f32_e64 v165, v141, v143
	v_mfma_f32_32x32x16_bf16 v[0:15], v[132:135], v[148:151], v[0:15]
	s_waitcnt lgkmcnt(4)
	v_mfma_f32_32x32x16_bf16 v[96:111], v[144:147], v[152:155], v[96:111]
	v_mfma_f32_32x32x16_bf16 v[16:31], v[132:135], v[152:155], v[16:31]
	s_waitcnt lgkmcnt(2)
	v_mfma_f32_32x32x16_bf16 v[80:95], v[144:147], v[156:159], v[80:95]
	v_mfma_f32_32x32x16_bf16 v[32:47], v[132:135], v[156:159], v[32:47]
	s_waitcnt lgkmcnt(0)
	v_mfma_f32_32x32x16_bf16 v[64:79], v[144:147], v[160:163], v[64:79]
	v_mfma_f32_32x32x16_bf16 v[48:63], v[132:135], v[160:163], v[48:63]
	s_nop 0
	ds_read_b64_tr_b16 v[132:133], v218 offset:28672
	ds_read_b64_tr_b16 v[134:135], v239 offset:30720
	ds_read_b64_tr_b16 v[140:141], v240 offset:28672
	ds_read_b64_tr_b16 v[142:143], v241 offset:30720
	ds_read_b64_tr_b16 v[144:145], v248 offset:28672
	ds_read_b64_tr_b16 v[146:147], v249 offset:30720
	ds_read_b64_tr_b16 v[148:149], v250 offset:28672
	ds_read_b64_tr_b16 v[150:151], v251 offset:30720
	s_waitcnt lgkmcnt(6)
	v_mfma_f32_32x32x16_bf16 v[112:127], v[128:131], v[132:135], v[112:127]
	v_mfma_f32_32x32x16_bf16 v[0:15], v[136:139], v[132:135], v[0:15]
	s_waitcnt lgkmcnt(4)
	v_mfma_f32_32x32x16_bf16 v[96:111], v[128:131], v[140:143], v[96:111]
	v_mfma_f32_32x32x16_bf16 v[16:31], v[136:139], v[140:143], v[16:31]
	s_waitcnt lgkmcnt(2)
	v_mfma_f32_32x32x16_bf16 v[80:95], v[128:131], v[144:147], v[80:95]
	v_mfma_f32_32x32x16_bf16 v[32:47], v[136:139], v[144:147], v[32:47]
	s_waitcnt lgkmcnt(0)
	v_mfma_f32_32x32x16_bf16 v[64:79], v[128:131], v[148:151], v[64:79]
	v_mfma_f32_32x32x16_bf16 v[48:63], v[136:139], v[148:151], v[48:63]
	s_waitcnt vmcnt(0)
	s_add_u32 s30, s30, 0x50000
	s_addc_u32 s31, s31, 0
	s_cmp_eq_u32 s45, s38
	s_mov_b32 s8, s39
	s_barrier
	s_cbranch_scc1 .LBB0_383
	s_branch .Lat2_top_O

; #define SB() __builtin_amdgcn_sched_barrier(0)
; #define EXPACK(sc_, rbq_, p0_, p1_) do { float ps_ = 0.f; \
;                 _Pragma("unroll") for (int r = 0; r < 16; ++r) { sc_[r] = __builtin_amdgcn_exp2f(SHIFT ? sc_[r] - bound2 : sc_[r]); ps_ += sc_[r]; } \
;                 lsum[rbq_] += ps_; p0_ = pack8(sc_, 0); p1_ = pack8(sc_, 1); } while (0)
; #define BLOAD(B_, ks_) do { asm volatile("" : "+v"(v0l)); _Pragma("unroll") for (int cb = 0; cb < 4; ++cb) B_[cb] = BFRAG(ks_, cb); SB(); } while (0)
; #define PVMMA(B_, pA_, pB_) do { _Pragma("unroll") for (int cb = 0; cb < 4; ++cb) { o[0][cb] = MFMA32(pA_, B_[cb], o[0][cb]); o[1][cb] = MFMA32(pB_, B_[cb], o[1][cb]); } } while (0)
; template <bool SHIFT> DI void phase_attn2(const Params& p, const Grp& G, int layer, LAS unsigned char* lds, int tid, int wave, int lane, int vcu, bool dry) {
;     ...
;             {
;                 f32x16 s0, s1; bf16x8 pa00, pa01, pa10, pa11; bf16x8 kfs[4], qfs[4];
;                 CHAIN(s0, 0, 0, true, true); CHAIN(s1, 0, 1, false, true);
;                 EXPACK(s0, 0, pa00, pa01); EXPACK(s1, 1, pa10, pa11);
;                 SB();
;                 CHAIN(s1, 1, 1, true, false); CHAIN(s0, 1, 0, false, true);
;                 bf16x8 pb00, pb01, pb10, pb11; bf16x8 B[4];
;                 BLOAD(B, 0);
;                 PVMMA(B, pa00, pa10); EXPACK(s0, 0, pb00, pb01);
;                 SB();
;                 BLOAD(B, 1);
;                 PVMMA(B, pa01, pa11); EXPACK(s1, 1, pb10, pb11);
;                 SB();
;                 BLOAD(B, 2);
;                 PVMMA(B, pb00, pb10);
.Lat2_body_O:
	ds_read_b128 v[128:131], v217 offset:32768
	ds_read_b128 v[160:163], v236 offset:32768
	ds_read_b128 v[166:169], v237 offset:32768
	ds_read_b128 v[170:173], v238 offset:32768
	ds_read_b128 v[132:135], v222
	ds_read_b128 v[136:139], v222 offset:1024
	ds_read_b128 v[140:143], v222 offset:2048
	ds_read_b128 v[174:177], v222 offset:3072
	s_waitcnt lgkmcnt(0)
	v_mfma_f32_32x32x16_bf16 v[144:159], v[128:131], v[132:135], 0
	v_mfma_f32_32x32x16_bf16 v[144:159], v[160:163], v[136:139], v[144:159]
	v_mfma_f32_32x32x16_bf16 v[144:159], v[166:169], v[140:143], v[144:159]
	v_mfma_f32_32x32x16_bf16 v[144:159], v[170:173], v[174:177], v[144:159]
	ds_read_b128 v[174:177], v222 offset:4096
	ds_read_b128 v[178:181], v222 offset:5120
	ds_read_b128 v[182:185], v222 offset:6144
	ds_read_b128 v[224:227], v222 offset:7168
	s_waitcnt lgkmcnt(0)
	v_mfma_f32_32x32x16_bf16 v[128:143], v[128:131], v[174:177], 0
	v_mfma_f32_32x32x16_bf16 v[128:143], v[160:163], v[178:181], v[128:143]
	v_mfma_f32_32x32x16_bf16 v[128:143], v[166:169], v[182:185], v[128:143]
	v_mfma_f32_32x32x16_bf16 v[128:143], v[170:173], v[224:227], v[128:143]
	s_nop 2
	v_exp_f32_e32 v144, v144
	v_exp_f32_e32 v145, v145
	v_exp_f32_e32 v146, v146
	v_exp_f32_e32 v147, v147
	v_exp_f32_e32 v148, v148
	s_nop 3
	v_exp_f32_e32 v189, v135
	v_exp_f32_e32 v149, v149
	v_add_f32_e32 v135, v145, v144
	v_exp_f32_e32 v150, v150
	v_exp_f32_e32 v188, v151
	v_exp_f32_e32 v128, v128
	v_exp_f32_e32 v129, v129
	v_exp_f32_e32 v130, v130
	v_exp_f32_e32 v131, v131
	v_exp_f32_e32 v132, v132
	v_exp_f32_e32 v133, v133
	v_exp_f32_e32 v134, v134
	v_add_f32_e32 v135, v146, v135
	v_add_f32_e32 v135, v147, v135
	v_add_f32_e32 v135, v148, v135
	v_add_f32_e32 v135, v149, v135
	v_exp_f32_e32 v208, v152
	v_exp_f32_e32 v206, v153
	v_exp_f32_e32 v204, v154
	v_exp_f32_e32 v202, v155
	v_exp_f32_e32 v200, v156
	v_exp_f32_e32 v198, v157
	v_exp_f32_e32 v196, v158
	v_exp_f32_e32 v190, v159
	v_cvt_pk_bf16_f32 v160, v144, v145
	v_cvt_pk_bf16_f32 v161, v146, v147
	v_cvt_pk_bf16_f32 v162, v148, v149
	v_cvt_pk_bf16_f32 v163, v150, v188
	v_exp_f32_e32 v209, v136
	v_exp_f32_e32 v207, v137
	v_exp_f32_e32 v205, v138
	v_exp_f32_e32 v203, v139
	v_exp_f32_e32 v201, v140
	v_exp_f32_e32 v199, v141
	v_exp_f32_e32 v197, v142
	v_exp_f32_e32 v191, v143
	v_add_f32_e32 v210, v150, v135
	v_cvt_pk_bf16_f32 v166, v128, v129
	v_cvt_pk_bf16_f32 v167, v130, v131
	v_cvt_pk_bf16_f32 v168, v132, v133
	v_cvt_pk_bf16_f32 v169, v134, v189
	ds_read_b128 v[144:147], v217 offset:40960
	ds_read_b128 v[170:173], v236 offset:40960
	ds_read_b128 v[228:231], v237 offset:40960
	ds_read_b128 v[232:235], v238 offset:40960
	v_add_f32_e32 v128, v129, v128
	v_add_f32_e32 v128, v130, v128
	v_add_f32_e32 v128, v131, v128
	v_add_f32_e32 v128, v132, v128
	v_add_f32_e32 v128, v133, v128
	v_add_f32_e32 v211, v134, v128
	s_waitcnt lgkmcnt(0)
	v_mfma_f32_32x32x16_bf16 v[128:143], v[144:147], v[174:177], 0
	v_mfma_f32_32x32x16_bf16 v[128:143], v[170:173], v[178:181], v[128:143]
	v_mfma_f32_32x32x16_bf16 v[128:143], v[228:231], v[182:185], v[128:143]
	v_mfma_f32_32x32x16_bf16 v[128:143], v[232:235], v[224:227], v[128:143]
	ds_read_b128 v[148:151], v222
	ds_read_b128 v[174:177], v222 offset:1024
	ds_read_b128 v[178:181], v222 offset:2048
	ds_read_b128 v[182:185], v222 offset:3072
	s_waitcnt lgkmcnt(0)
	v_mfma_f32_32x32x16_bf16 v[144:159], v[144:147], v[148:151], 0
	v_mfma_f32_32x32x16_bf16 v[144:159], v[170:173], v[174:177], v[144:159]
	v_mfma_f32_32x32x16_bf16 v[144:159], v[228:231], v[178:181], v[144:159]
	v_mfma_f32_32x32x16_bf16 v[144:159], v[232:235], v[182:185], v[144:159]
	s_nop 4
	ds_read_b64_tr_b16 v[170:171], v218 offset:49152
	ds_read_b64_tr_b16 v[172:173], v239 offset:51200
	ds_read_b64_tr_b16 v[174:175], v240 offset:49152
	ds_read_b64_tr_b16 v[176:177], v241 offset:51200
	ds_read_b64_tr_b16 v[178:179], v248 offset:49152
	ds_read_b64_tr_b16 v[180:181], v249 offset:51200
	ds_read_b64_tr_b16 v[182:183], v250 offset:49152
	ds_read_b64_tr_b16 v[184:185], v251 offset:51200
	v_exp_f32_e32 v144, v144
	s_waitcnt lgkmcnt(6)
	v_mfma_f32_32x32x16_bf16 v[112:127], v[160:163], v[170:173], v[112:127]
	v_exp_f32_e32 v145, v145
	v_exp_f32_e32 v146, v146
	v_exp_f32_e32 v147, v147
	v_exp_f32_e32 v148, v148
	v_exp_f32_e32 v149, v149
	v_mfma_f32_32x32x16_bf16 v[0:15], v[166:169], v[170:173], v[0:15]
	v_exp_f32_e32 v170, v151
	v_exp_f32_e32 v172, v154
	s_waitcnt lgkmcnt(4)
	v_mfma_f32_32x32x16_bf16 v[96:111], v[160:163], v[174:177], v[96:111]
	v_mfma_f32_32x32x16_bf16 v[16:31], v[166:169], v[174:177], v[16:31]
	v_exp_f32_e32 v174, v153
	v_exp_f32_e32 v176, v156
	s_waitcnt lgkmcnt(2)
	v_mfma_f32_32x32x16_bf16 v[80:95], v[160:163], v[178:181], v[80:95]
	v_mfma_f32_32x32x16_bf16 v[32:47], v[166:169], v[178:181], v[32:47]
	v_exp_f32_e32 v178, v155
	v_exp_f32_e32 v180, v158
	s_waitcnt lgkmcnt(0)
; #define SB() __builtin_amdgcn_sched_barrier(0)
; #define EXPACK(sc_, rbq_, p0_, p1_) do { float ps_ = 0.f; \
;                 _Pragma("unroll") for (int r = 0; r < 16; ++r) { sc_[r] = __builtin_amdgcn_exp2f(SHIFT ? sc_[r] - bound2 : sc_[r]); ps_ += sc_[r]; } \
;                 lsum[rbq_] += ps_; p0_ = pack8(sc_, 0); p1_ = pack8(sc_, 1); } while (0)
; #define BLOAD(B_, ks_) do { asm volatile("" : "+v"(v0l)); _Pragma("unroll") for (int cb = 0; cb < 4; ++cb) B_[cb] = BFRAG(ks_, cb); SB(); } while (0)
; #define PVMMA(B_, pA_, pB_) do { _Pragma("unroll") for (int cb = 0; cb < 4; ++cb) { o[0][cb] = MFMA32(pA_, B_[cb], o[0][cb]); o[1][cb] = MFMA32(pB_, B_[cb], o[1][cb]); } } while (0)
; template <bool SHIFT> DI void phase_attn2(const Params& p, const Grp& G, int layer, LAS unsigned char* lds, int tid, int wave, int lane, int vcu, bool dry) {
;     ...
;                 PVMMA(B, pa00, pa10); EXPACK(s0, 0, pb00, pb01);
;                 SB();
;                 BLOAD(B, 1);
;                 PVMMA(B, pa01, pa11); EXPACK(s1, 1, pb10, pb11);
;                 SB();
;                 BLOAD(B, 2);
;                 PVMMA(B, pb00, pb10);
;                 SB();
;                 BLOAD(B, 3);
;                 PVMMA(B, pb01, pb11);
;                 SB();
;             }
;     ...
;             asm volatile("s_waitcnt vmcnt(0)" ::: "memory");
;             __syncthreads();
	v_mfma_f32_32x32x16_bf16 v[64:79], v[160:163], v[182:185], v[64:79]
	v_add_f32_e32 v160, v145, v144
	v_add_f32_e32 v160, v146, v160
	v_add_f32_e32 v160, v147, v160
	v_add_f32_e32 v160, v148, v160
	v_add_f32_e32 v186, v149, v160
	v_cvt_pk_bf16_f32 v144, v144, v145
	v_mfma_f32_32x32x16_bf16 v[48:63], v[166:169], v[182:185], v[48:63]
	v_exp_f32_e32 v166, v150
	v_exp_f32_e32 v168, v152
	v_exp_f32_e32 v182, v157
	v_exp_f32_e32 v184, v159
	v_cvt_pk_bf16_f32 v145, v146, v147
	v_cvt_pk_bf16_f32 v146, v148, v149
	s_nop 0
	ds_read_b64_tr_b16 v[160:161], v218 offset:53248
	ds_read_b64_tr_b16 v[162:163], v239 offset:55296
	ds_read_b64_tr_b16 v[156:157], v240 offset:53248
	ds_read_b64_tr_b16 v[158:159], v241 offset:55296
	ds_read_b64_tr_b16 v[152:153], v248 offset:53248
	ds_read_b64_tr_b16 v[154:155], v249 offset:55296
	ds_read_b64_tr_b16 v[148:149], v250 offset:53248
	ds_read_b64_tr_b16 v[150:151], v251 offset:55296
	v_exp_f32_e32 v223, v128
	v_exp_f32_e32 v224, v129
	v_exp_f32_e32 v225, v130
	v_exp_f32_e32 v226, v131
	v_exp_f32_e32 v227, v132
	v_add_f32_e32 v128, v224, v223
	v_exp_f32_e32 v228, v133
	v_exp_f32_e32 v167, v134
	v_exp_f32_e32 v171, v135
	v_cvt_pk_bf16_f32 v132, v208, v206
	v_cvt_pk_bf16_f32 v133, v204, v202
	v_cvt_pk_bf16_f32 v134, v200, v198
	v_cvt_pk_bf16_f32 v135, v196, v190
	v_add_f32_e32 v128, v225, v128
	v_exp_f32_e32 v169, v136
	v_exp_f32_e32 v175, v137
	v_exp_f32_e32 v173, v138
	v_exp_f32_e32 v179, v139
	v_cvt_pk_bf16_f32 v136, v209, v207
	v_cvt_pk_bf16_f32 v137, v205, v203
	v_cvt_pk_bf16_f32 v138, v201, v199
	v_cvt_pk_bf16_f32 v139, v197, v191
	v_add_f32_e32 v128, v226, v128
	v_add_f32_e32 v128, v227, v128
	v_add_f32_e32 v187, v228, v128
	v_pk_add_f32 v[128:129], v[188:189], v[210:211]
	s_waitcnt lgkmcnt(6)
	v_mfma_f32_32x32x16_bf16 v[112:127], v[132:135], v[160:163], v[112:127]
	v_add_f32_e64 v128, v208, v128
	v_add_f32_e64 v129, v209, v129
	v_exp_f32_e32 v177, v140
	v_pk_add_f32 v[128:129], v[206:207], v[128:129]
	v_exp_f32_e32 v183, v141
	v_pk_add_f32 v[128:129], v[204:205], v[128:129]
	v_exp_f32_e32 v181, v142
	v_pk_add_f32 v[128:129], v[202:203], v[128:129]
	s_waitcnt lgkmcnt(4)
	v_mfma_f32_32x32x16_bf16 v[96:111], v[132:135], v[156:159], v[96:111]
	v_exp_f32_e32 v185, v143
	v_pk_add_f32 v[128:129], v[200:201], v[128:129]
	v_cvt_pk_bf16_f32 v147, v166, v170
	v_pk_add_f32 v[128:129], v[198:199], v[128:129]
	v_cvt_pk_bf16_f32 v130, v176, v182
	v_pk_add_f32 v[128:129], v[196:197], v[128:129]
	v_cvt_pk_bf16_f32 v131, v180, v184
	s_waitcnt lgkmcnt(2)
	v_mfma_f32_32x32x16_bf16 v[80:95], v[132:135], v[152:155], v[80:95]
	v_add_f32_e64 v128, v190, v128
	v_add_f32_e64 v129, v191, v129
	v_add_f32_e64 v140, v164, v128
	v_add_f32_e64 v141, v165, v129
	v_cvt_pk_bf16_f32 v128, v168, v174
	v_cvt_pk_bf16_f32 v129, v172, v178
	s_waitcnt lgkmcnt(0)
	v_mfma_f32_32x32x16_bf16 v[64:79], v[132:135], v[148:151], v[64:79]
	v_add_f32_e64 v132, v166, v186
	v_add_f32_e64 v133, v167, v187
	v_cvt_pk_bf16_f32 v134, v227, v228
	v_add_f32_e64 v132, v170, v132
	v_add_f32_e64 v133, v171, v133
	v_cvt_pk_bf16_f32 v135, v167, v171
	v_pk_add_f32 v[132:133], v[168:169], v[132:133]
	s_nop 0
	v_pk_add_f32 v[132:133], v[174:175], v[132:133]
	v_mfma_f32_32x32x16_bf16 v[0:15], v[136:139], v[160:163], v[0:15]
	v_add_f32_e64 v132, v172, v132
	v_add_f32_e64 v133, v173, v133
	v_add_f32_e64 v132, v178, v132
	v_add_f32_e64 v133, v179, v133
	v_add_f32_e64 v132, v176, v132
	v_add_f32_e64 v133, v177, v133
	v_pk_add_f32 v[132:133], v[182:183], v[132:133]
	v_mfma_f32_32x32x16_bf16 v[16:31], v[136:139], v[156:159], v[16:31]
	v_add_f32_e64 v132, v180, v132
	v_add_f32_e64 v133, v181, v133
	v_add_f32_e64 v142, v184, v132
	v_add_f32_e64 v143, v185, v133
	v_cvt_pk_bf16_f32 v132, v223, v224
	v_cvt_pk_bf16_f32 v133, v225, v226
	v_mfma_f32_32x32x16_bf16 v[32:47], v[136:139], v[152:155], v[32:47]
	v_mfma_f32_32x32x16_bf16 v[48:63], v[136:139], v[148:151], v[48:63]
	v_cvt_pk_bf16_f32 v136, v169, v175
	v_cvt_pk_bf16_f32 v137, v173, v179
	v_cvt_pk_bf16_f32 v138, v177, v183
	v_cvt_pk_bf16_f32 v139, v181, v185
	s_nop 0
	ds_read_b64_tr_b16 v[148:149], v218 offset:57344
	ds_read_b64_tr_b16 v[150:151], v239 offset:59392
	ds_read_b64_tr_b16 v[152:153], v240 offset:57344
	ds_read_b64_tr_b16 v[154:155], v241 offset:59392
	ds_read_b64_tr_b16 v[156:157], v248 offset:57344
	ds_read_b64_tr_b16 v[158:159], v249 offset:59392
	ds_read_b64_tr_b16 v[160:161], v250 offset:57344
	ds_read_b64_tr_b16 v[162:163], v251 offset:59392
	s_waitcnt lgkmcnt(6)
	v_mfma_f32_32x32x16_bf16 v[112:127], v[144:147], v[148:151], v[112:127]
	v_add_f32_e64 v164, v140, v142
	v_add_f32_e64 v165, v141, v143
	v_mfma_f32_32x32x16_bf16 v[0:15], v[132:135], v[148:151], v[0:15]
	s_waitcnt lgkmcnt(4)
	v_mfma_f32_32x32x16_bf16 v[96:111], v[144:147], v[152:155], v[96:111]
	v_mfma_f32_32x32x16_bf16 v[16:31], v[132:135], v[152:155], v[16:31]
	s_waitcnt lgkmcnt(2)
	v_mfma_f32_32x32x16_bf16 v[80:95], v[144:147], v[156:159], v[80:95]
	v_mfma_f32_32x32x16_bf16 v[32:47], v[132:135], v[156:159], v[32:47]
	s_waitcnt lgkmcnt(0)
	v_mfma_f32_32x32x16_bf16 v[64:79], v[144:147], v[160:163], v[64:79]
	v_mfma_f32_32x32x16_bf16 v[48:63], v[132:135], v[160:163], v[48:63]
	s_nop 0
	ds_read_b64_tr_b16 v[132:133], v218 offset:61440
	ds_read_b64_tr_b16 v[134:135], v239 offset:63488
	ds_read_b64_tr_b16 v[140:141], v240 offset:61440
	ds_read_b64_tr_b16 v[142:143], v241 offset:63488
	ds_read_b64_tr_b16 v[144:145], v248 offset:61440
	ds_read_b64_tr_b16 v[146:147], v249 offset:63488
	ds_read_b64_tr_b16 v[148:149], v250 offset:61440
	ds_read_b64_tr_b16 v[150:151], v251 offset:63488
	s_waitcnt lgkmcnt(6)
	v_mfma_f32_32x32x16_bf16 v[112:127], v[128:131], v[132:135], v[112:127]
	v_mfma_f32_32x32x16_bf16 v[0:15], v[136:139], v[132:135], v[0:15]
	s_waitcnt lgkmcnt(4)
	v_mfma_f32_32x32x16_bf16 v[96:111], v[128:131], v[140:143], v[96:111]
	v_mfma_f32_32x32x16_bf16 v[16:31], v[136:139], v[140:143], v[16:31]
	s_waitcnt lgkmcnt(2)
	v_mfma_f32_32x32x16_bf16 v[80:95], v[128:131], v[144:147], v[80:95]
	v_mfma_f32_32x32x16_bf16 v[32:47], v[136:139], v[144:147], v[32:47]
	s_waitcnt lgkmcnt(0)
	v_mfma_f32_32x32x16_bf16 v[64:79], v[128:131], v[148:151], v[64:79]
	v_mfma_f32_32x32x16_bf16 v[48:63], v[136:139], v[148:151], v[48:63]
	s_waitcnt vmcnt(0)
	s_add_u32 s30, s30, 0x50000
	s_addc_u32 s31, s31, 0
	s_cmp_eq_u32 s45, s38
	s_mov_b32 s8, s39
	s_barrier
	s_cbranch_scc1 .LBB0_383
	s_branch .LBB0_379
